# GLA step A: v-image staging issues its 4 loads before the LDS writes (was load, vmcnt(0), write per trip); on top of mem staging
# speedup vs baseline: 1.0080x; 1.0051x over previous
.LBB0_457:
	v_mov_b64_e32 v[120:121], s[8:9]
	v_and_b32_e32 v10, 0xf8, v25
	v_mad_i64_i32 v[120:121], s[16:17], v23, s22, v[120:121]
	v_lshlrev_b32_e32 v10, 1, v10
	v_lshl_add_u64 v[120:121], v[120:121], 0, s[10:11]
	v_lshl_add_u64 v[120:121], v[120:121], 0, v[10:11]
	v_add_co_u32_e32 v120, vcc, 0x1000, v120
	v_add_u32_e32 v25, 0x1000, v25
	s_nop 0
	v_addc_co_u32_e32 v121, vcc, 0, v121, vcc
	global_load_dwordx4 v[104:107], v[120:121], off offset:2048
	v_add_u32_e32 v23, 16, v23
	v_mov_b64_e32 v[120:121], s[8:9]
	v_and_b32_e32 v10, 0xf8, v25
	v_mad_i64_i32 v[120:121], s[16:17], v23, s22, v[120:121]
	v_lshlrev_b32_e32 v10, 1, v10
	v_lshl_add_u64 v[120:121], v[120:121], 0, s[10:11]
	v_lshl_add_u64 v[120:121], v[120:121], 0, v[10:11]
	v_add_co_u32_e32 v120, vcc, 0x1000, v120
	v_add_u32_e32 v25, 0x1000, v25
	s_nop 0
	v_addc_co_u32_e32 v121, vcc, 0, v121, vcc
	global_load_dwordx4 v[108:111], v[120:121], off offset:2048
	v_add_u32_e32 v23, 16, v23
	v_mov_b64_e32 v[120:121], s[8:9]
	v_and_b32_e32 v10, 0xf8, v25
	v_mad_i64_i32 v[120:121], s[16:17], v23, s22, v[120:121]
	v_lshlrev_b32_e32 v10, 1, v10
	v_lshl_add_u64 v[120:121], v[120:121], 0, s[10:11]
	v_lshl_add_u64 v[120:121], v[120:121], 0, v[10:11]
	v_add_co_u32_e32 v120, vcc, 0x1000, v120
	v_add_u32_e32 v25, 0x1000, v25
	s_nop 0
	v_addc_co_u32_e32 v121, vcc, 0, v121, vcc
	global_load_dwordx4 v[112:115], v[120:121], off offset:2048
	v_add_u32_e32 v23, 16, v23
	v_mov_b64_e32 v[120:121], s[8:9]
	v_and_b32_e32 v10, 0xf8, v25
	v_mad_i64_i32 v[120:121], s[16:17], v23, s22, v[120:121]
	v_lshlrev_b32_e32 v10, 1, v10
	v_lshl_add_u64 v[120:121], v[120:121], 0, s[10:11]
	v_lshl_add_u64 v[120:121], v[120:121], 0, v[10:11]
	v_add_co_u32_e32 v120, vcc, 0x1000, v120
	v_add_u32_e32 v25, 0x1000, v25
	s_nop 0
	v_addc_co_u32_e32 v121, vcc, 0, v121, vcc
	global_load_dwordx4 v[116:119], v[120:121], off offset:2048
	v_add_u32_e32 v23, 16, v23
	s_waitcnt vmcnt(3)
	ds_write_b128 v27, v[104:107]
	v_add_u32_e32 v27, 0x2100, v27
	s_waitcnt vmcnt(2)
	ds_write_b128 v27, v[108:111]
	v_add_u32_e32 v27, 0x2100, v27
	s_waitcnt vmcnt(1)
	ds_write_b128 v27, v[112:115]
	v_add_u32_e32 v27, 0x2100, v27
	s_waitcnt vmcnt(0)
	ds_write_b128 v27, v[116:119]
	v_add_u32_e32 v27, 0x2100, v27
	s_or_b64 exec, exec, s[14:15]
	v_or_b32_e32 v10, s30, v29
	v_readlane_b32 s36, v249, 0
	v_lshlrev_b32_e32 v10, 2, v10
	v_readlane_b32 s48, v249, 12
	v_readlane_b32 s49, v249, 13
	s_waitcnt lgkmcnt(0)
	s_barrier
	v_lshl_add_u64 v[108:109], s[48:49], 0, v[10:11]
	v_add_co_u32_e32 v96, vcc, 0x1000, v108
	s_nop 1
	v_addc_co_u32_e32 v97, vcc, 0, v109, vcc
	v_add_co_u32_e32 v98, vcc, 0x2000, v108
	v_readlane_b32 s50, v249, 14
	s_nop 0
	v_addc_co_u32_e32 v99, vcc, 0, v109, vcc
	v_add_co_u32_e32 v102, vcc, 0x3000, v108
	v_readlane_b32 s51, v249, 15
	s_nop 0
	v_addc_co_u32_e32 v103, vcc, 0, v109, vcc
	v_add_co_u32_e32 v110, vcc, 0x4000, v108
	v_readlane_b32 s37, v249, 1
	s_nop 0
	v_addc_co_u32_e32 v111, vcc, 0, v109, vcc
	global_load_dword v26, v10, s[48:49]
	global_load_dword v25, v10, s[48:49] offset:2048
	global_load_dword v23, v10, s[50:51]
	global_load_dword v107, v[96:97], off
	global_load_dword v106, v[96:97], off offset:2048
	global_load_dword v104, v[98:99], off
	global_load_dword v101, v[98:99], off offset:2048
	s_nop 0
	global_load_dword v98, v[102:103], off
	global_load_dword v96, v[102:103], off offset:2048
	global_load_dword v95, v[110:111], off
	global_load_dword v27, v[110:111], off offset:2048
	v_add_co_u32_e32 v102, vcc, 0x5000, v108
	v_mov_b32_e32 v10, 0
	s_nop 0
	v_addc_co_u32_e32 v103, vcc, 0, v109, vcc
	v_add_co_u32_e32 v110, vcc, 0x6000, v108
	v_readlane_b32 s38, v249, 2
	s_nop 0
	v_addc_co_u32_e32 v111, vcc, 0, v109, vcc
	global_load_dword v105, v[102:103], off
	s_nop 0
	global_load_dword v102, v[102:103], off offset:2048
	s_nop 0
	global_load_dword v99, v[110:111], off
	global_load_dword v97, v[110:111], off offset:2048
	v_add_co_u32_e32 v108, vcc, 0x7000, v108
	v_readlane_b32 s39, v249, 3
	s_nop 0
	v_addc_co_u32_e32 v109, vcc, 0, v109, vcc
	global_load_dword v103, v[108:109], off
	global_load_dword v100, v[108:109], off offset:2048
	ds_read_b128 v[108:111], v55
	ds_read_b128 v[112:115], v55 offset:16
	ds_read_b128 v[116:119], v55 offset:32
	ds_read_b128 v[120:123], v55 offset:48
	ds_read_b128 v[124:127], v56
	ds_read_b128 v[128:131], v56 offset:16
	ds_read_b128 v[132:135], v56 offset:32
	ds_read_b128 v[136:139], v56 offset:48
	ds_read_b128 v[140:143], v57
	v_readlane_b32 s40, v249, 4
	v_readlane_b32 s41, v249, 5
	v_readlane_b32 s42, v249, 6
	v_readlane_b32 s43, v249, 7
	v_readlane_b32 s44, v249, 8
	v_readlane_b32 s45, v249, 9
	v_readlane_b32 s46, v249, 10
	v_readlane_b32 s47, v249, 11
	s_waitcnt vmcnt(14) lgkmcnt(8)
	v_fma_f32 v108, v26, v108, v23
	v_fmac_f32_e32 v108, v25, v109
	s_waitcnt vmcnt(13)
	v_fmac_f32_e32 v108, v107, v110
	s_waitcnt vmcnt(12)
	v_fmac_f32_e32 v108, v106, v111
	s_waitcnt vmcnt(11) lgkmcnt(7)
	v_fmac_f32_e32 v108, v104, v112
	s_waitcnt vmcnt(10)
	v_fmac_f32_e32 v108, v101, v113
	s_waitcnt vmcnt(9)
	v_fmac_f32_e32 v108, v98, v114
	s_waitcnt lgkmcnt(4)
	v_fma_f32 v124, v26, v124, v23
	s_waitcnt vmcnt(8)
	v_fmac_f32_e32 v108, v96, v115
	v_fmac_f32_e32 v124, v25, v125
	s_waitcnt vmcnt(7)
	v_fmac_f32_e32 v108, v95, v116
	v_fmac_f32_e32 v124, v107, v126
	s_waitcnt vmcnt(6)
	v_fmac_f32_e32 v108, v27, v117
	v_fmac_f32_e32 v124, v106, v127
	s_waitcnt lgkmcnt(3)
	v_fmac_f32_e32 v124, v104, v128
	v_fmac_f32_e32 v124, v101, v129
	s_waitcnt vmcnt(5)
	v_fmac_f32_e32 v108, v105, v118
	s_waitcnt vmcnt(4)
	v_fmac_f32_e32 v108, v102, v119
	s_waitcnt vmcnt(3)
	v_fmac_f32_e32 v108, v99, v120
	v_fmac_f32_e32 v124, v98, v130
	s_waitcnt vmcnt(2)
	v_fmac_f32_e32 v108, v97, v121
	v_fmac_f32_e32 v124, v96, v131
	s_waitcnt lgkmcnt(2)
	v_fmac_f32_e32 v124, v95, v132
	v_fmac_f32_e32 v124, v27, v133
	s_waitcnt vmcnt(1)
	v_fmac_f32_e32 v108, v103, v122
	s_waitcnt vmcnt(0)
	v_fmac_f32_e32 v108, v100, v123
	v_mul_f32_e64 v109, |v108|, s25
	v_fmac_f32_e32 v124, v105, v134
	v_exp_f32_e32 v109, v109
	v_fmac_f32_e32 v124, v102, v135
	s_waitcnt lgkmcnt(1)
	v_fmac_f32_e32 v124, v99, v136
	v_fmac_f32_e32 v124, v97, v137
	v_fmac_f32_e32 v124, v103, v138
	v_add_f32_e32 v109, 1.0, v109
	v_fmac_f32_e32 v124, v100, v139
	v_log_f32_e32 v109, v109
	v_mul_f32_e64 v110, |v124|, s25
	v_exp_f32_e32 v110, v110
	v_min_f32_e32 v108, 0, v108
	v_fmac_f32_e32 v108, 0xbf317218, v109
	v_fma_f32 v108, v108, s26, 0
	v_add_f32_e32 v110, 1.0, v110
	ds_write_b32 v78, v108 offset:4096
	s_waitcnt lgkmcnt(1)
	v_fma_f32 v109, v26, v140, v23
	v_log_f32_e32 v122, v110
	ds_read_b128 v[110:113], v57 offset:16
	ds_read_b128 v[114:117], v57 offset:32
	ds_read_b128 v[118:121], v57 offset:48
	v_fmac_f32_e32 v109, v25, v141
	v_fmac_f32_e32 v109, v107, v142
	v_fmac_f32_e32 v109, v106, v143
	s_waitcnt lgkmcnt(2)
	v_fmac_f32_e32 v109, v104, v110
	v_fmac_f32_e32 v109, v101, v111
	v_fmac_f32_e32 v109, v98, v112
	v_fmac_f32_e32 v109, v96, v113
	s_waitcnt lgkmcnt(1)
	v_fmac_f32_e32 v109, v95, v114
	v_fmac_f32_e32 v109, v27, v115
	v_fmac_f32_e32 v109, v105, v116
	v_fmac_f32_e32 v109, v102, v117
	s_waitcnt lgkmcnt(0)
	v_fmac_f32_e32 v109, v99, v118
	v_fmac_f32_e32 v109, v97, v119
	v_fmac_f32_e32 v109, v103, v120
	v_fmac_f32_e32 v109, v100, v121
	v_mul_f32_e64 v110, |v109|, s25
	v_exp_f32_e32 v110, v110
	v_min_f32_e32 v111, 0, v124
	v_fmac_f32_e32 v111, 0xbf317218, v122
	v_fmac_f32_e32 v108, 0x3d800000, v111
	v_add_f32_e32 v110, 1.0, v110
	v_log_f32_e32 v114, v110
	ds_read_b128 v[110:113], v58
	ds_write_b32 v79, v108 offset:4096
	v_min_f32_e32 v109, 0, v109
	v_fmac_f32_e32 v109, 0xbf317218, v114
	ds_read_b128 v[114:117], v58 offset:16
	ds_read_b128 v[118:121], v58 offset:32
	ds_read_b128 v[122:125], v58 offset:48
	s_waitcnt lgkmcnt(4)
	v_fma_f32 v110, v26, v110, v23
	v_fmac_f32_e32 v110, v25, v111
	v_fmac_f32_e32 v110, v107, v112
	v_fmac_f32_e32 v110, v106, v113
	s_waitcnt lgkmcnt(2)
	v_fmac_f32_e32 v110, v104, v114
	v_fmac_f32_e32 v110, v101, v115
	v_fmac_f32_e32 v110, v98, v116
	v_fmac_f32_e32 v110, v96, v117
	s_waitcnt lgkmcnt(1)
	v_fmac_f32_e32 v110, v95, v118
	v_fmac_f32_e32 v110, v27, v119
	v_fmac_f32_e32 v110, v105, v120
	v_fmac_f32_e32 v110, v102, v121
	s_waitcnt lgkmcnt(0)
	v_fmac_f32_e32 v110, v99, v122
	v_fmac_f32_e32 v110, v97, v123
	v_fmac_f32_e32 v110, v103, v124
	v_fmac_f32_e32 v110, v100, v125
	v_mul_f32_e64 v111, |v110|, s25
	v_exp_f32_e32 v111, v111
	v_fmac_f32_e32 v108, 0x3d800000, v109
	v_min_f32_e32 v109, 0, v110
	ds_write_b32 v80, v108 offset:4096
	v_add_f32_e32 v114, 1.0, v111
	ds_read_b128 v[110:113], v59
	v_log_f32_e32 v126, v114
	ds_read_b128 v[114:117], v59 offset:16
	ds_read_b128 v[118:121], v59 offset:32
	ds_read_b128 v[122:125], v59 offset:48
	s_waitcnt lgkmcnt(3)
	v_fma_f32 v127, v26, v110, v23
	v_fmac_f32_e32 v127, v25, v111
	v_fmac_f32_e32 v127, v107, v112
	v_fmac_f32_e32 v127, v106, v113
	s_waitcnt lgkmcnt(2)
	v_fmac_f32_e32 v127, v104, v114
	v_fmac_f32_e32 v127, v101, v115
	v_fmac_f32_e32 v127, v98, v116
	v_fmac_f32_e32 v127, v96, v117
	s_waitcnt lgkmcnt(1)
	v_fmac_f32_e32 v127, v95, v118
	v_fmac_f32_e32 v127, v27, v119
	v_fmac_f32_e32 v127, v105, v120
	v_fmac_f32_e32 v127, v102, v121
	s_waitcnt lgkmcnt(0)
	v_fmac_f32_e32 v127, v99, v122
	v_fmac_f32_e32 v127, v97, v123
	v_fmac_f32_e32 v127, v103, v124
	v_fmac_f32_e32 v127, v100, v125
	v_mul_f32_e64 v110, |v127|, s25
	v_exp_f32_e32 v110, v110
	v_fmac_f32_e32 v109, 0xbf317218, v126
	v_fmac_f32_e32 v108, 0x3d800000, v109
	ds_write_b32 v81, v108 offset:4096
	v_add_f32_e32 v109, 1.0, v110
	ds_read_b128 v[110:113], v60
	ds_read_b128 v[114:117], v60 offset:16
	ds_read_b128 v[118:121], v60 offset:32
	ds_read_b128 v[122:125], v60 offset:48
	v_log_f32_e32 v109, v109
	s_waitcnt lgkmcnt(3)
	v_fma_f32 v110, v26, v110, v23
	v_fmac_f32_e32 v110, v25, v111
	v_fmac_f32_e32 v110, v107, v112
	v_fmac_f32_e32 v110, v106, v113
	s_waitcnt lgkmcnt(2)
	v_fmac_f32_e32 v110, v104, v114
	v_fmac_f32_e32 v110, v101, v115
	v_fmac_f32_e32 v110, v98, v116
	v_fmac_f32_e32 v110, v96, v117
	s_waitcnt lgkmcnt(1)
	v_fmac_f32_e32 v110, v95, v118
	v_fmac_f32_e32 v110, v27, v119
	v_fmac_f32_e32 v110, v105, v120
	v_fmac_f32_e32 v110, v102, v121
	s_waitcnt lgkmcnt(0)
	v_fmac_f32_e32 v110, v99, v122
	v_fmac_f32_e32 v110, v97, v123
	v_fmac_f32_e32 v110, v103, v124
	v_fmac_f32_e32 v110, v100, v125
	v_mul_f32_e64 v111, |v110|, s25
	v_exp_f32_e32 v111, v111
	v_min_f32_e32 v112, 0, v127
	v_fmac_f32_e32 v112, 0xbf317218, v109
	v_fmac_f32_e32 v108, 0x3d800000, v112
	v_add_f32_e32 v109, 1.0, v111
	v_min_f32_e32 v126, 0, v110
	ds_read_b128 v[110:113], v61
	v_log_f32_e32 v109, v109
	ds_write_b32 v82, v108 offset:4096
	ds_read_b128 v[114:117], v61 offset:16
	ds_read_b128 v[118:121], v61 offset:32
	ds_read_b128 v[122:125], v61 offset:48
	v_fmac_f32_e32 v126, 0xbf317218, v109
	s_waitcnt lgkmcnt(4)
	v_fma_f32 v109, v26, v110, v23
	v_fmac_f32_e32 v109, v25, v111
	v_fmac_f32_e32 v109, v107, v112
	v_fmac_f32_e32 v109, v106, v113
	s_waitcnt lgkmcnt(2)
	v_fmac_f32_e32 v109, v104, v114
	v_fmac_f32_e32 v109, v101, v115
	v_fmac_f32_e32 v109, v98, v116
	v_fmac_f32_e32 v109, v96, v117
	s_waitcnt lgkmcnt(1)
	v_fmac_f32_e32 v109, v95, v118
	v_fmac_f32_e32 v109, v27, v119
	v_fmac_f32_e32 v109, v105, v120
	v_fmac_f32_e32 v109, v102, v121
	s_waitcnt lgkmcnt(0)
	v_fmac_f32_e32 v109, v99, v122
	v_fmac_f32_e32 v109, v97, v123
	v_fmac_f32_e32 v109, v103, v124
	v_fmac_f32_e32 v109, v100, v125
	v_mul_f32_e64 v110, |v109|, s25
	v_exp_f32_e32 v110, v110
	v_fmac_f32_e32 v108, 0x3d800000, v126
	ds_write_b32 v83, v108 offset:4096
	v_min_f32_e32 v109, 0, v109
	v_add_f32_e32 v114, 1.0, v110
	ds_read_b128 v[110:113], v62
	v_log_f32_e32 v126, v114
	ds_read_b128 v[114:117], v62 offset:16
	ds_read_b128 v[118:121], v62 offset:32
	ds_read_b128 v[122:125], v62 offset:48
	s_waitcnt lgkmcnt(3)
	v_fma_f32 v127, v26, v110, v23
	v_fmac_f32_e32 v127, v25, v111
	v_fmac_f32_e32 v127, v107, v112
	v_fmac_f32_e32 v127, v106, v113
	s_waitcnt lgkmcnt(2)
	v_fmac_f32_e32 v127, v104, v114
	v_fmac_f32_e32 v127, v101, v115
	v_fmac_f32_e32 v127, v98, v116
	v_fmac_f32_e32 v127, v96, v117
	s_waitcnt lgkmcnt(1)
	v_fmac_f32_e32 v127, v95, v118
	v_fmac_f32_e32 v127, v27, v119
	v_fmac_f32_e32 v127, v105, v120
	v_fmac_f32_e32 v127, v102, v121
	s_waitcnt lgkmcnt(0)
	v_fmac_f32_e32 v127, v99, v122
	v_fmac_f32_e32 v127, v97, v123
	v_fmac_f32_e32 v127, v103, v124
	v_fmac_f32_e32 v127, v100, v125
	v_mul_f32_e64 v110, |v127|, s25
	v_exp_f32_e32 v110, v110
	v_fmac_f32_e32 v109, 0xbf317218, v126
	v_fmac_f32_e32 v108, 0x3d800000, v109
	ds_write_b32 v84, v108 offset:4096
	v_add_f32_e32 v109, 1.0, v110
	ds_read_b128 v[110:113], v63
	ds_read_b128 v[114:117], v63 offset:16
	ds_read_b128 v[118:121], v63 offset:32
	ds_read_b128 v[122:125], v63 offset:48
	v_log_f32_e32 v109, v109
	s_waitcnt lgkmcnt(3)
	v_fma_f32 v110, v26, v110, v23
	v_fmac_f32_e32 v110, v25, v111
	v_fmac_f32_e32 v110, v107, v112
	v_fmac_f32_e32 v110, v106, v113
	s_waitcnt lgkmcnt(2)
	v_fmac_f32_e32 v110, v104, v114
	v_fmac_f32_e32 v110, v101, v115
	v_fmac_f32_e32 v110, v98, v116
	v_fmac_f32_e32 v110, v96, v117
	s_waitcnt lgkmcnt(1)
	v_fmac_f32_e32 v110, v95, v118
	v_fmac_f32_e32 v110, v27, v119
	v_fmac_f32_e32 v110, v105, v120
	v_fmac_f32_e32 v110, v102, v121
	s_waitcnt lgkmcnt(0)
	v_fmac_f32_e32 v110, v99, v122
	v_fmac_f32_e32 v110, v97, v123
	v_fmac_f32_e32 v110, v103, v124
	v_fmac_f32_e32 v110, v100, v125
	v_mul_f32_e64 v111, |v110|, s25
	v_exp_f32_e32 v111, v111
	v_min_f32_e32 v112, 0, v127
	v_fmac_f32_e32 v112, 0xbf317218, v109
	v_fmac_f32_e32 v108, 0x3d800000, v112
	v_add_f32_e32 v109, 1.0, v111
	v_min_f32_e32 v126, 0, v110
	ds_read_b128 v[110:113], v64
	v_log_f32_e32 v109, v109
	ds_write_b32 v85, v108 offset:4096
	ds_read_b128 v[114:117], v64 offset:16
	ds_read_b128 v[118:121], v64 offset:32
	ds_read_b128 v[122:125], v64 offset:48
	v_fmac_f32_e32 v126, 0xbf317218, v109
	s_waitcnt lgkmcnt(4)
	v_fma_f32 v109, v26, v110, v23
	v_fmac_f32_e32 v109, v25, v111
	v_fmac_f32_e32 v109, v107, v112
	v_fmac_f32_e32 v109, v106, v113
	s_waitcnt lgkmcnt(2)
	v_fmac_f32_e32 v109, v104, v114
	v_fmac_f32_e32 v109, v101, v115
	v_fmac_f32_e32 v109, v98, v116
	v_fmac_f32_e32 v109, v96, v117
	s_waitcnt lgkmcnt(1)
	v_fmac_f32_e32 v109, v95, v118
	v_fmac_f32_e32 v109, v27, v119
	v_fmac_f32_e32 v109, v105, v120
	v_fmac_f32_e32 v109, v102, v121
	s_waitcnt lgkmcnt(0)
	v_fmac_f32_e32 v109, v99, v122
	v_fmac_f32_e32 v109, v97, v123
	v_fmac_f32_e32 v109, v103, v124
	v_fmac_f32_e32 v109, v100, v125
	v_mul_f32_e64 v110, |v109|, s25
	v_exp_f32_e32 v110, v110
	v_fmac_f32_e32 v108, 0x3d800000, v126
	ds_write_b32 v86, v108 offset:4096
	v_min_f32_e32 v109, 0, v109
	v_add_f32_e32 v114, 1.0, v110
	ds_read_b128 v[110:113], v65
	v_log_f32_e32 v126, v114
	ds_read_b128 v[114:117], v65 offset:16
	ds_read_b128 v[118:121], v65 offset:32
	ds_read_b128 v[122:125], v65 offset:48
	s_waitcnt lgkmcnt(3)
	v_fma_f32 v127, v26, v110, v23
	v_fmac_f32_e32 v127, v25, v111
	v_fmac_f32_e32 v127, v107, v112
	v_fmac_f32_e32 v127, v106, v113
	s_waitcnt lgkmcnt(2)
	v_fmac_f32_e32 v127, v104, v114
	v_fmac_f32_e32 v127, v101, v115
	v_fmac_f32_e32 v127, v98, v116
	v_fmac_f32_e32 v127, v96, v117
	s_waitcnt lgkmcnt(1)
	v_fmac_f32_e32 v127, v95, v118
	v_fmac_f32_e32 v127, v27, v119
	v_fmac_f32_e32 v127, v105, v120
	v_fmac_f32_e32 v127, v102, v121
	s_waitcnt lgkmcnt(0)
	v_fmac_f32_e32 v127, v99, v122
	v_fmac_f32_e32 v127, v97, v123
	v_fmac_f32_e32 v127, v103, v124
	v_fmac_f32_e32 v127, v100, v125
	v_mul_f32_e64 v110, |v127|, s25
	v_exp_f32_e32 v110, v110
	v_fmac_f32_e32 v109, 0xbf317218, v126
	v_fmac_f32_e32 v108, 0x3d800000, v109
	ds_write_b32 v87, v108 offset:4096
	v_add_f32_e32 v109, 1.0, v110
	ds_read_b128 v[110:113], v66
	ds_read_b128 v[114:117], v66 offset:16
	ds_read_b128 v[118:121], v66 offset:32
	ds_read_b128 v[122:125], v66 offset:48
	v_log_f32_e32 v109, v109
	s_waitcnt lgkmcnt(3)
	v_fma_f32 v110, v26, v110, v23
	v_fmac_f32_e32 v110, v25, v111
	v_fmac_f32_e32 v110, v107, v112
	v_fmac_f32_e32 v110, v106, v113
	s_waitcnt lgkmcnt(2)
	v_fmac_f32_e32 v110, v104, v114
	v_fmac_f32_e32 v110, v101, v115
	v_fmac_f32_e32 v110, v98, v116
	v_fmac_f32_e32 v110, v96, v117
	s_waitcnt lgkmcnt(1)
	v_fmac_f32_e32 v110, v95, v118
	v_fmac_f32_e32 v110, v27, v119
	v_fmac_f32_e32 v110, v105, v120
	v_fmac_f32_e32 v110, v102, v121
	s_waitcnt lgkmcnt(0)
	v_fmac_f32_e32 v110, v99, v122
	v_fmac_f32_e32 v110, v97, v123
	v_fmac_f32_e32 v110, v103, v124
	v_fmac_f32_e32 v110, v100, v125
	v_mul_f32_e64 v111, |v110|, s25
	v_exp_f32_e32 v111, v111
	v_min_f32_e32 v112, 0, v127
	v_fmac_f32_e32 v112, 0xbf317218, v109
	v_fmac_f32_e32 v108, 0x3d800000, v112
	v_add_f32_e32 v109, 1.0, v111
	v_min_f32_e32 v126, 0, v110
	ds_read_b128 v[110:113], v67
	v_log_f32_e32 v109, v109
	ds_write_b32 v88, v108 offset:4096
	ds_read_b128 v[114:117], v67 offset:16
	ds_read_b128 v[118:121], v67 offset:32
	ds_read_b128 v[122:125], v67 offset:48
	v_fmac_f32_e32 v126, 0xbf317218, v109
	s_waitcnt lgkmcnt(4)
	v_fma_f32 v109, v26, v110, v23
	v_fmac_f32_e32 v109, v25, v111
	v_fmac_f32_e32 v109, v107, v112
	v_fmac_f32_e32 v109, v106, v113
	s_waitcnt lgkmcnt(2)
	v_fmac_f32_e32 v109, v104, v114
	v_fmac_f32_e32 v109, v101, v115
	v_fmac_f32_e32 v109, v98, v116
	v_fmac_f32_e32 v109, v96, v117
	s_waitcnt lgkmcnt(1)
	v_fmac_f32_e32 v109, v95, v118
	v_fmac_f32_e32 v109, v27, v119
	v_fmac_f32_e32 v109, v105, v120
	v_fmac_f32_e32 v109, v102, v121
	s_waitcnt lgkmcnt(0)
	v_fmac_f32_e32 v109, v99, v122
	v_fmac_f32_e32 v109, v97, v123
	v_fmac_f32_e32 v109, v103, v124
	v_fmac_f32_e32 v109, v100, v125
	v_mul_f32_e64 v110, |v109|, s25
	v_exp_f32_e32 v110, v110
	v_fmac_f32_e32 v108, 0x3d800000, v126
	ds_write_b32 v89, v108 offset:4096
	v_min_f32_e32 v109, 0, v109
	v_add_f32_e32 v114, 1.0, v110
	ds_read_b128 v[110:113], v68
	v_log_f32_e32 v126, v114
	ds_read_b128 v[114:117], v68 offset:16
	ds_read_b128 v[118:121], v68 offset:32
	ds_read_b128 v[122:125], v68 offset:48
	s_waitcnt lgkmcnt(3)
	v_fma_f32 v127, v26, v110, v23
	v_fmac_f32_e32 v127, v25, v111
	v_fmac_f32_e32 v127, v107, v112
	v_fmac_f32_e32 v127, v106, v113
	s_waitcnt lgkmcnt(2)
	v_fmac_f32_e32 v127, v104, v114
	v_fmac_f32_e32 v127, v101, v115
	v_fmac_f32_e32 v127, v98, v116
	v_fmac_f32_e32 v127, v96, v117
	s_waitcnt lgkmcnt(1)
	v_fmac_f32_e32 v127, v95, v118
	v_fmac_f32_e32 v127, v27, v119
	v_fmac_f32_e32 v127, v105, v120
	v_fmac_f32_e32 v127, v102, v121
	s_waitcnt lgkmcnt(0)
	v_fmac_f32_e32 v127, v99, v122
	v_fmac_f32_e32 v127, v97, v123
	v_fmac_f32_e32 v127, v103, v124
	v_fmac_f32_e32 v127, v100, v125
	v_mul_f32_e64 v110, |v127|, s25
	v_exp_f32_e32 v110, v110
	v_fmac_f32_e32 v109, 0xbf317218, v126
	v_fmac_f32_e32 v108, 0x3d800000, v109
	ds_write_b32 v90, v108 offset:4096
	v_add_f32_e32 v109, 1.0, v110
	ds_read_b128 v[110:113], v69
	ds_read_b128 v[114:117], v69 offset:16
	ds_read_b128 v[118:121], v69 offset:32
	ds_read_b128 v[122:125], v69 offset:48
	v_log_f32_e32 v109, v109
	s_waitcnt lgkmcnt(3)
	v_fma_f32 v126, v26, v110, v23
	v_fmac_f32_e32 v126, v25, v111
	v_fmac_f32_e32 v126, v107, v112
	v_fmac_f32_e32 v126, v106, v113
	s_waitcnt lgkmcnt(2)
	v_fmac_f32_e32 v126, v104, v114
	v_fmac_f32_e32 v126, v101, v115
	v_fmac_f32_e32 v126, v98, v116
	v_fmac_f32_e32 v126, v96, v117
	s_waitcnt lgkmcnt(1)
	v_fmac_f32_e32 v126, v95, v118
	v_fmac_f32_e32 v126, v27, v119
	v_fmac_f32_e32 v126, v105, v120
	v_fmac_f32_e32 v126, v102, v121
	s_waitcnt lgkmcnt(0)
	v_fmac_f32_e32 v126, v99, v122
	v_fmac_f32_e32 v126, v97, v123
	v_fmac_f32_e32 v126, v103, v124
	v_fmac_f32_e32 v126, v100, v125
	v_mul_f32_e64 v110, |v126|, s25
	v_exp_f32_e32 v110, v110
	v_min_f32_e32 v111, 0, v127
	v_fmac_f32_e32 v111, 0xbf317218, v109
	v_fmac_f32_e32 v108, 0x3d800000, v111
	v_add_f32_e32 v109, 1.0, v110
	ds_read_b128 v[110:113], v70
	ds_read_b128 v[114:117], v70 offset:16
	ds_read_b128 v[118:121], v70 offset:32
	ds_read_b128 v[122:125], v70 offset:48
	v_log_f32_e32 v109, v109
	ds_write_b32 v91, v108 offset:4096
	s_waitcnt lgkmcnt(4)
	v_fmac_f32_e32 v23, v26, v110
	v_fmac_f32_e32 v23, v25, v111
	v_fmac_f32_e32 v23, v107, v112
	v_fmac_f32_e32 v23, v106, v113
	s_waitcnt lgkmcnt(3)
	v_fmac_f32_e32 v23, v104, v114
	v_fmac_f32_e32 v23, v101, v115
	v_fmac_f32_e32 v23, v98, v116
	v_fmac_f32_e32 v23, v96, v117
	s_waitcnt lgkmcnt(2)
	v_fmac_f32_e32 v23, v95, v118
	v_fmac_f32_e32 v23, v27, v119
	v_fmac_f32_e32 v23, v105, v120
	v_fmac_f32_e32 v23, v102, v121
	s_waitcnt lgkmcnt(1)
	v_fmac_f32_e32 v23, v99, v122
	v_fmac_f32_e32 v23, v97, v123
	v_fmac_f32_e32 v23, v103, v124
	v_fmac_f32_e32 v23, v100, v125
	v_mul_f32_e64 v25, |v23|, s25
	v_exp_f32_e32 v25, v25
	v_min_f32_e32 v26, 0, v126
	v_fmac_f32_e32 v26, 0xbf317218, v109
	v_min_f32_e32 v23, 0, v23
	v_add_f32_e32 v25, 1.0, v25
	v_log_f32_e32 v25, v25
	v_fmac_f32_e32 v108, 0x3d800000, v26
	ds_write_b32 v92, v108 offset:4096
	v_fmac_f32_e32 v23, 0xbf317218, v25
	v_fmac_f32_e32 v108, 0x3d800000, v23
	ds_write_b32 v93, v108 offset:4096
	ds_write_b32 v192, v108 offset:36864
	s_waitcnt lgkmcnt(0)
	s_barrier
	s_and_saveexec_b64 s[14:15], s[4:5]
	s_cbranch_execz .LBB0_462
	v_mov_b32_e32 v10, 0
	s_mov_b64 s[16:17], 0
	v_mov_b32_e32 v23, v54
	v_mov_b32_e32 v25, v30

.LBB0_1240:
	v_mov_b64_e32 v[120:121], s[2:3]
	v_and_b32_e32 v10, 0xf8, v25
	v_mad_i64_i32 v[120:121], s[16:17], v23, s23, v[120:121]
	v_lshlrev_b32_e32 v10, 1, v10
	v_lshl_add_u64 v[120:121], v[120:121], 0, s[10:11]
	v_lshl_add_u64 v[120:121], v[120:121], 0, v[10:11]
	v_add_co_u32_e32 v120, vcc, 0x1000, v120
	v_add_u32_e32 v25, 0x1000, v25
	s_nop 0
	v_addc_co_u32_e32 v121, vcc, 0, v121, vcc
	global_load_dwordx4 v[104:107], v[120:121], off offset:2048
	v_add_u32_e32 v23, 16, v23
	v_mov_b64_e32 v[120:121], s[2:3]
	v_and_b32_e32 v10, 0xf8, v25
	v_mad_i64_i32 v[120:121], s[16:17], v23, s23, v[120:121]
	v_lshlrev_b32_e32 v10, 1, v10
	v_lshl_add_u64 v[120:121], v[120:121], 0, s[10:11]
	v_lshl_add_u64 v[120:121], v[120:121], 0, v[10:11]
	v_add_co_u32_e32 v120, vcc, 0x1000, v120
	v_add_u32_e32 v25, 0x1000, v25
	s_nop 0
	v_addc_co_u32_e32 v121, vcc, 0, v121, vcc
	global_load_dwordx4 v[108:111], v[120:121], off offset:2048
	v_add_u32_e32 v23, 16, v23
	v_mov_b64_e32 v[120:121], s[2:3]
	v_and_b32_e32 v10, 0xf8, v25
	v_mad_i64_i32 v[120:121], s[16:17], v23, s23, v[120:121]
	v_lshlrev_b32_e32 v10, 1, v10
	v_lshl_add_u64 v[120:121], v[120:121], 0, s[10:11]
	v_lshl_add_u64 v[120:121], v[120:121], 0, v[10:11]
	v_add_co_u32_e32 v120, vcc, 0x1000, v120
	v_add_u32_e32 v25, 0x1000, v25
	s_nop 0
	v_addc_co_u32_e32 v121, vcc, 0, v121, vcc
	global_load_dwordx4 v[112:115], v[120:121], off offset:2048
	v_add_u32_e32 v23, 16, v23
	v_mov_b64_e32 v[120:121], s[2:3]
	v_and_b32_e32 v10, 0xf8, v25
	v_mad_i64_i32 v[120:121], s[16:17], v23, s23, v[120:121]
	v_lshlrev_b32_e32 v10, 1, v10
	v_lshl_add_u64 v[120:121], v[120:121], 0, s[10:11]
	v_lshl_add_u64 v[120:121], v[120:121], 0, v[10:11]
	v_add_co_u32_e32 v120, vcc, 0x1000, v120
	v_add_u32_e32 v25, 0x1000, v25
	s_nop 0
	v_addc_co_u32_e32 v121, vcc, 0, v121, vcc
	global_load_dwordx4 v[116:119], v[120:121], off offset:2048
	v_add_u32_e32 v23, 16, v23
	s_waitcnt vmcnt(3)
	ds_write_b128 v27, v[104:107]
	v_add_u32_e32 v27, 0x2100, v27
	s_waitcnt vmcnt(2)
	ds_write_b128 v27, v[108:111]
	v_add_u32_e32 v27, 0x2100, v27
	s_waitcnt vmcnt(1)
	ds_write_b128 v27, v[112:115]
	v_add_u32_e32 v27, 0x2100, v27
	s_waitcnt vmcnt(0)
	ds_write_b128 v27, v[116:119]
	v_add_u32_e32 v27, 0x2100, v27
	s_or_b64 exec, exec, s[14:15]
	v_or_b32_e32 v10, s33, v29
	v_readlane_b32 s36, v249, 0
	v_lshlrev_b32_e32 v10, 2, v10
	v_readlane_b32 s48, v249, 12
	v_readlane_b32 s49, v249, 13
	s_waitcnt lgkmcnt(0)
	s_barrier
	v_lshl_add_u64 v[108:109], s[48:49], 0, v[10:11]
	v_add_co_u32_e32 v26, vcc, 0x8000, v108
	s_nop 1
	v_addc_co_u32_e32 v27, vcc, 0, v109, vcc
	v_add_co_u32_e32 v100, vcc, s22, v108
	v_readlane_b32 s50, v249, 14
	s_nop 0
	v_addc_co_u32_e32 v101, vcc, 0, v109, vcc
	v_add_co_u32_e32 v102, vcc, 0xa000, v108
	v_readlane_b32 s51, v249, 15
	s_nop 0
	v_addc_co_u32_e32 v103, vcc, 0, v109, vcc
	v_add_co_u32_e32 v104, vcc, 0xb000, v108
	v_readlane_b32 s37, v249, 1
	s_nop 0
	v_addc_co_u32_e32 v105, vcc, 0, v109, vcc
	global_load_dword v98, v[26:27], off
	global_load_dword v97, v[26:27], off offset:2048
	global_load_dword v95, v[100:101], off
	global_load_dword v94, v[100:101], off offset:2048
	s_nop 0
	global_load_dword v26, v[102:103], off
	global_load_dword v23, v[102:103], off offset:2048
	global_load_dword v27, v[104:105], off
	global_load_dword v25, v[104:105], off offset:2048
	global_load_dword v96, v10, s[50:51] offset:2048
	v_add_co_u32_e32 v100, vcc, s24, v108
	v_mov_b32_e32 v10, 0
	s_nop 0
	v_addc_co_u32_e32 v101, vcc, 0, v109, vcc
	v_add_co_u32_e32 v110, vcc, 0xd000, v108
	v_readlane_b32 s38, v249, 2
	s_nop 0
	v_addc_co_u32_e32 v111, vcc, 0, v109, vcc
	v_add_co_u32_e32 v112, vcc, 0xe000, v108
	v_readlane_b32 s39, v249, 3
	s_nop 0
	v_addc_co_u32_e32 v113, vcc, 0, v109, vcc
	global_load_dword v106, v[100:101], off
	global_load_dword v105, v[100:101], off offset:2048
	global_load_dword v103, v[110:111], off
	s_nop 0
	global_load_dword v101, v[110:111], off offset:2048
	global_load_dword v99, v[112:113], off
	v_add_co_u32_e32 v108, vcc, 0xf000, v108
	v_readlane_b32 s40, v249, 4
	s_nop 0
	v_addc_co_u32_e32 v109, vcc, 0, v109, vcc
	global_load_dword v104, v[112:113], off offset:2048
	global_load_dword v102, v[108:109], off
	global_load_dword v100, v[108:109], off offset:2048
	ds_read_b128 v[108:111], v54
	ds_read_b128 v[112:115], v54 offset:16
	ds_read_b128 v[116:119], v54 offset:32
	ds_read_b128 v[120:123], v54 offset:48
	ds_read_b128 v[124:127], v55
	ds_read_b128 v[128:131], v55 offset:16
	ds_read_b128 v[132:135], v55 offset:32
	ds_read_b128 v[136:139], v55 offset:48
	v_readlane_b32 s41, v249, 5
	v_readlane_b32 s42, v249, 6
	v_readlane_b32 s43, v249, 7
	v_readlane_b32 s44, v249, 8
	v_readlane_b32 s45, v249, 9
	v_readlane_b32 s46, v249, 10
	v_readlane_b32 s47, v249, 11
	s_waitcnt vmcnt(8) lgkmcnt(7)
	v_fma_f32 v107, v98, v108, v96
	v_fmac_f32_e32 v107, v97, v109
	v_fmac_f32_e32 v107, v95, v110
	v_fmac_f32_e32 v107, v94, v111
	s_waitcnt lgkmcnt(6)
	v_fmac_f32_e32 v107, v26, v112
	s_waitcnt lgkmcnt(3)
	v_fma_f32 v124, v98, v124, v96
	v_fmac_f32_e32 v107, v23, v113
	v_fmac_f32_e32 v124, v97, v125
	v_fmac_f32_e32 v107, v27, v114
	v_fmac_f32_e32 v124, v95, v126
	v_fmac_f32_e32 v107, v25, v115
	v_fmac_f32_e32 v124, v94, v127
	s_waitcnt vmcnt(7)
	v_fmac_f32_e32 v107, v106, v116
	s_waitcnt lgkmcnt(2)
	v_fmac_f32_e32 v124, v26, v128
	s_waitcnt vmcnt(6)
	v_fmac_f32_e32 v107, v105, v117
	v_fmac_f32_e32 v124, v23, v129
	s_waitcnt vmcnt(5)
	v_fmac_f32_e32 v107, v103, v118
	v_fmac_f32_e32 v124, v27, v130
	s_waitcnt vmcnt(4)
	v_fmac_f32_e32 v107, v101, v119
	v_fmac_f32_e32 v124, v25, v131
	s_waitcnt vmcnt(3)
	v_fmac_f32_e32 v107, v99, v120
	s_waitcnt lgkmcnt(1)
	v_fmac_f32_e32 v124, v106, v132
	s_waitcnt vmcnt(2)
	v_fmac_f32_e32 v107, v104, v121
	v_fmac_f32_e32 v124, v105, v133
	s_waitcnt vmcnt(1)
	v_fmac_f32_e32 v107, v102, v122
	v_fmac_f32_e32 v124, v103, v134
	s_waitcnt vmcnt(0)
	v_fmac_f32_e32 v107, v100, v123
	v_fmac_f32_e32 v124, v101, v135
	v_mul_f32_e64 v108, |v107|, s27
	s_waitcnt lgkmcnt(0)
	v_fmac_f32_e32 v124, v99, v136
	v_exp_f32_e32 v108, v108
	v_fmac_f32_e32 v124, v104, v137
	v_fmac_f32_e32 v124, v102, v138
	v_fmac_f32_e32 v124, v100, v139
	v_add_f32_e32 v108, 1.0, v108
	v_mul_f32_e64 v109, |v124|, s27
	v_log_f32_e32 v108, v108
	v_exp_f32_e32 v109, v109
	v_min_f32_e32 v107, 0, v107
	v_fmac_f32_e32 v107, 0xbf317218, v108
	v_add_f32_e32 v112, 1.0, v109
	ds_read_b128 v[108:111], v56
	v_fma_f32 v107, v107, s28, 0
	ds_write_b32 v77, v107 offset:4096
	v_log_f32_e32 v125, v112
	ds_read_b128 v[112:115], v56 offset:16
	ds_read_b128 v[116:119], v56 offset:32
	ds_read_b128 v[120:123], v56 offset:48
	s_waitcnt lgkmcnt(4)
	v_fma_f32 v108, v98, v108, v96
	v_fmac_f32_e32 v108, v97, v109
	v_fmac_f32_e32 v108, v95, v110
	v_fmac_f32_e32 v108, v94, v111
	s_waitcnt lgkmcnt(2)
	v_fmac_f32_e32 v108, v26, v112
	v_fmac_f32_e32 v108, v23, v113
	v_fmac_f32_e32 v108, v27, v114
	v_fmac_f32_e32 v108, v25, v115
	s_waitcnt lgkmcnt(1)
	v_fmac_f32_e32 v108, v106, v116
	v_fmac_f32_e32 v108, v105, v117
	v_fmac_f32_e32 v108, v103, v118
	v_fmac_f32_e32 v108, v101, v119
	s_waitcnt lgkmcnt(0)
	v_fmac_f32_e32 v108, v99, v120
	v_fmac_f32_e32 v108, v104, v121
	v_fmac_f32_e32 v108, v102, v122
	v_fmac_f32_e32 v108, v100, v123
	v_mul_f32_e64 v109, |v108|, s27
	v_exp_f32_e32 v109, v109
	v_min_f32_e32 v110, 0, v124
	v_fmac_f32_e32 v110, 0xbf317218, v125
	v_fmac_f32_e32 v107, 0x3d800000, v110
	v_add_f32_e32 v109, 1.0, v109
	v_log_f32_e32 v112, v109
	v_min_f32_e32 v124, 0, v108
	ds_read_b128 v[108:111], v57
	ds_write_b32 v78, v107 offset:4096
	v_fmac_f32_e32 v124, 0xbf317218, v112
	ds_read_b128 v[112:115], v57 offset:16
	ds_read_b128 v[116:119], v57 offset:32
	ds_read_b128 v[120:123], v57 offset:48
	v_fmac_f32_e32 v107, 0x3d800000, v124
	s_waitcnt lgkmcnt(4)
	v_fma_f32 v108, v98, v108, v96
	v_fmac_f32_e32 v108, v97, v109
	v_fmac_f32_e32 v108, v95, v110
	v_fmac_f32_e32 v108, v94, v111
	s_waitcnt lgkmcnt(2)
	v_fmac_f32_e32 v108, v26, v112
	v_fmac_f32_e32 v108, v23, v113
	v_fmac_f32_e32 v108, v27, v114
	v_fmac_f32_e32 v108, v25, v115
	s_waitcnt lgkmcnt(1)
	v_fmac_f32_e32 v108, v106, v116
	v_fmac_f32_e32 v108, v105, v117
	v_fmac_f32_e32 v108, v103, v118
	v_fmac_f32_e32 v108, v101, v119
	s_waitcnt lgkmcnt(0)
	v_fmac_f32_e32 v108, v99, v120
	v_fmac_f32_e32 v108, v104, v121
	v_fmac_f32_e32 v108, v102, v122
	v_fmac_f32_e32 v108, v100, v123
	v_mul_f32_e64 v109, |v108|, s27
	v_exp_f32_e32 v109, v109
	v_min_f32_e32 v124, 0, v108
	ds_write_b32 v79, v107 offset:4096
	v_add_f32_e32 v112, 1.0, v109
	ds_read_b128 v[108:111], v58
	v_log_f32_e32 v125, v112
	ds_read_b128 v[112:115], v58 offset:16
	ds_read_b128 v[116:119], v58 offset:32
	ds_read_b128 v[120:123], v58 offset:48
	s_waitcnt lgkmcnt(3)
	v_fma_f32 v126, v98, v108, v96
	v_fmac_f32_e32 v126, v97, v109
	v_fmac_f32_e32 v126, v95, v110
	v_fmac_f32_e32 v126, v94, v111
	s_waitcnt lgkmcnt(2)
	v_fmac_f32_e32 v126, v26, v112
	v_fmac_f32_e32 v126, v23, v113
	v_fmac_f32_e32 v126, v27, v114
	v_fmac_f32_e32 v126, v25, v115
	s_waitcnt lgkmcnt(1)
	v_fmac_f32_e32 v126, v106, v116
	v_fmac_f32_e32 v126, v105, v117
	v_fmac_f32_e32 v126, v103, v118
	v_fmac_f32_e32 v126, v101, v119
	s_waitcnt lgkmcnt(0)
	v_fmac_f32_e32 v126, v99, v120
	v_fmac_f32_e32 v126, v104, v121
	v_fmac_f32_e32 v126, v102, v122
	v_fmac_f32_e32 v126, v100, v123
	v_mul_f32_e64 v108, |v126|, s27
	v_exp_f32_e32 v108, v108
	v_fmac_f32_e32 v124, 0xbf317218, v125
	v_fmac_f32_e32 v107, 0x3d800000, v124
	ds_write_b32 v80, v107 offset:4096
	v_add_f32_e32 v112, 1.0, v108
	ds_read_b128 v[108:111], v59
	v_log_f32_e32 v124, v112
	ds_read_b128 v[112:115], v59 offset:16
	ds_read_b128 v[116:119], v59 offset:32
	ds_read_b128 v[120:123], v59 offset:48
	s_waitcnt lgkmcnt(3)
	v_fma_f32 v108, v98, v108, v96
	v_fmac_f32_e32 v108, v97, v109
	v_fmac_f32_e32 v108, v95, v110
	v_fmac_f32_e32 v108, v94, v111
	s_waitcnt lgkmcnt(2)
	v_fmac_f32_e32 v108, v26, v112
	v_fmac_f32_e32 v108, v23, v113
	v_fmac_f32_e32 v108, v27, v114
	v_fmac_f32_e32 v108, v25, v115
	s_waitcnt lgkmcnt(1)
	v_fmac_f32_e32 v108, v106, v116
	v_fmac_f32_e32 v108, v105, v117
	v_fmac_f32_e32 v108, v103, v118
	v_fmac_f32_e32 v108, v101, v119
	s_waitcnt lgkmcnt(0)
	v_fmac_f32_e32 v108, v99, v120
	v_fmac_f32_e32 v108, v104, v121
	v_fmac_f32_e32 v108, v102, v122
	v_fmac_f32_e32 v108, v100, v123
	v_mul_f32_e64 v109, |v108|, s27
	v_exp_f32_e32 v109, v109
	v_min_f32_e32 v110, 0, v126
	v_fmac_f32_e32 v110, 0xbf317218, v124
	v_fmac_f32_e32 v107, 0x3d800000, v110
	v_add_f32_e32 v109, 1.0, v109
	v_log_f32_e32 v112, v109
	v_min_f32_e32 v124, 0, v108
	ds_read_b128 v[108:111], v60
	ds_write_b32 v81, v107 offset:4096
	v_fmac_f32_e32 v124, 0xbf317218, v112
	ds_read_b128 v[112:115], v60 offset:16
	ds_read_b128 v[116:119], v60 offset:32
	ds_read_b128 v[120:123], v60 offset:48
	v_fmac_f32_e32 v107, 0x3d800000, v124
	s_waitcnt lgkmcnt(4)
	v_fma_f32 v108, v98, v108, v96
	v_fmac_f32_e32 v108, v97, v109
	v_fmac_f32_e32 v108, v95, v110
	v_fmac_f32_e32 v108, v94, v111
	s_waitcnt lgkmcnt(2)
	v_fmac_f32_e32 v108, v26, v112
	v_fmac_f32_e32 v108, v23, v113
	v_fmac_f32_e32 v108, v27, v114
	v_fmac_f32_e32 v108, v25, v115
	s_waitcnt lgkmcnt(1)
	v_fmac_f32_e32 v108, v106, v116
	v_fmac_f32_e32 v108, v105, v117
	v_fmac_f32_e32 v108, v103, v118
	v_fmac_f32_e32 v108, v101, v119
	s_waitcnt lgkmcnt(0)
	v_fmac_f32_e32 v108, v99, v120
	v_fmac_f32_e32 v108, v104, v121
	v_fmac_f32_e32 v108, v102, v122
	v_fmac_f32_e32 v108, v100, v123
	v_mul_f32_e64 v109, |v108|, s27
	v_exp_f32_e32 v109, v109
	v_min_f32_e32 v124, 0, v108
	ds_write_b32 v82, v107 offset:4096
	v_add_f32_e32 v112, 1.0, v109
	ds_read_b128 v[108:111], v61
	v_log_f32_e32 v125, v112
	ds_read_b128 v[112:115], v61 offset:16
	ds_read_b128 v[116:119], v61 offset:32
	ds_read_b128 v[120:123], v61 offset:48
	s_waitcnt lgkmcnt(3)
	v_fma_f32 v126, v98, v108, v96
	v_fmac_f32_e32 v126, v97, v109
	v_fmac_f32_e32 v126, v95, v110
	v_fmac_f32_e32 v126, v94, v111
	s_waitcnt lgkmcnt(2)
	v_fmac_f32_e32 v126, v26, v112
	v_fmac_f32_e32 v126, v23, v113
	v_fmac_f32_e32 v126, v27, v114
	v_fmac_f32_e32 v126, v25, v115
	s_waitcnt lgkmcnt(1)
	v_fmac_f32_e32 v126, v106, v116
	v_fmac_f32_e32 v126, v105, v117
	v_fmac_f32_e32 v126, v103, v118
	v_fmac_f32_e32 v126, v101, v119
	s_waitcnt lgkmcnt(0)
	v_fmac_f32_e32 v126, v99, v120
	v_fmac_f32_e32 v126, v104, v121
	v_fmac_f32_e32 v126, v102, v122
	v_fmac_f32_e32 v126, v100, v123
	v_mul_f32_e64 v108, |v126|, s27
	v_exp_f32_e32 v108, v108
	v_fmac_f32_e32 v124, 0xbf317218, v125
	v_fmac_f32_e32 v107, 0x3d800000, v124
	ds_write_b32 v83, v107 offset:4096
	v_add_f32_e32 v112, 1.0, v108
	ds_read_b128 v[108:111], v62
	v_log_f32_e32 v124, v112
	ds_read_b128 v[112:115], v62 offset:16
	ds_read_b128 v[116:119], v62 offset:32
	ds_read_b128 v[120:123], v62 offset:48
	s_waitcnt lgkmcnt(3)
	v_fma_f32 v108, v98, v108, v96
	v_fmac_f32_e32 v108, v97, v109
	v_fmac_f32_e32 v108, v95, v110
	v_fmac_f32_e32 v108, v94, v111
	s_waitcnt lgkmcnt(2)
	v_fmac_f32_e32 v108, v26, v112
	v_fmac_f32_e32 v108, v23, v113
	v_fmac_f32_e32 v108, v27, v114
	v_fmac_f32_e32 v108, v25, v115
	s_waitcnt lgkmcnt(1)
	v_fmac_f32_e32 v108, v106, v116
	v_fmac_f32_e32 v108, v105, v117
	v_fmac_f32_e32 v108, v103, v118
	v_fmac_f32_e32 v108, v101, v119
	s_waitcnt lgkmcnt(0)
	v_fmac_f32_e32 v108, v99, v120
	v_fmac_f32_e32 v108, v104, v121
	v_fmac_f32_e32 v108, v102, v122
	v_fmac_f32_e32 v108, v100, v123
	v_mul_f32_e64 v109, |v108|, s27
	v_exp_f32_e32 v109, v109
	v_min_f32_e32 v110, 0, v126
	v_fmac_f32_e32 v110, 0xbf317218, v124
	v_fmac_f32_e32 v107, 0x3d800000, v110
	v_add_f32_e32 v109, 1.0, v109
	v_log_f32_e32 v112, v109
	v_min_f32_e32 v124, 0, v108
	ds_read_b128 v[108:111], v63
	ds_write_b32 v84, v107 offset:4096
	v_fmac_f32_e32 v124, 0xbf317218, v112
	ds_read_b128 v[112:115], v63 offset:16
	ds_read_b128 v[116:119], v63 offset:32
	ds_read_b128 v[120:123], v63 offset:48
	v_fmac_f32_e32 v107, 0x3d800000, v124
	s_waitcnt lgkmcnt(4)
	v_fma_f32 v108, v98, v108, v96
	v_fmac_f32_e32 v108, v97, v109
	v_fmac_f32_e32 v108, v95, v110
	v_fmac_f32_e32 v108, v94, v111
	s_waitcnt lgkmcnt(2)
	v_fmac_f32_e32 v108, v26, v112
	v_fmac_f32_e32 v108, v23, v113
	v_fmac_f32_e32 v108, v27, v114
	v_fmac_f32_e32 v108, v25, v115
	s_waitcnt lgkmcnt(1)
	v_fmac_f32_e32 v108, v106, v116
	v_fmac_f32_e32 v108, v105, v117
	v_fmac_f32_e32 v108, v103, v118
	v_fmac_f32_e32 v108, v101, v119
	s_waitcnt lgkmcnt(0)
	v_fmac_f32_e32 v108, v99, v120
	v_fmac_f32_e32 v108, v104, v121
	v_fmac_f32_e32 v108, v102, v122
	v_fmac_f32_e32 v108, v100, v123
	v_mul_f32_e64 v109, |v108|, s27
	v_exp_f32_e32 v109, v109
	v_min_f32_e32 v124, 0, v108
	ds_write_b32 v85, v107 offset:4096
	v_add_f32_e32 v112, 1.0, v109
	ds_read_b128 v[108:111], v64
	v_log_f32_e32 v125, v112
	ds_read_b128 v[112:115], v64 offset:16
	ds_read_b128 v[116:119], v64 offset:32
	ds_read_b128 v[120:123], v64 offset:48
	s_waitcnt lgkmcnt(3)
	v_fma_f32 v126, v98, v108, v96
	v_fmac_f32_e32 v126, v97, v109
	v_fmac_f32_e32 v126, v95, v110
	v_fmac_f32_e32 v126, v94, v111
	s_waitcnt lgkmcnt(2)
	v_fmac_f32_e32 v126, v26, v112
	v_fmac_f32_e32 v126, v23, v113
	v_fmac_f32_e32 v126, v27, v114
	v_fmac_f32_e32 v126, v25, v115
	s_waitcnt lgkmcnt(1)
	v_fmac_f32_e32 v126, v106, v116
	v_fmac_f32_e32 v126, v105, v117
	v_fmac_f32_e32 v126, v103, v118
	v_fmac_f32_e32 v126, v101, v119
	s_waitcnt lgkmcnt(0)
	v_fmac_f32_e32 v126, v99, v120
	v_fmac_f32_e32 v126, v104, v121
	v_fmac_f32_e32 v126, v102, v122
	v_fmac_f32_e32 v126, v100, v123
	v_mul_f32_e64 v108, |v126|, s27
	v_exp_f32_e32 v108, v108
	v_fmac_f32_e32 v124, 0xbf317218, v125
	v_fmac_f32_e32 v107, 0x3d800000, v124
	ds_write_b32 v86, v107 offset:4096
	v_add_f32_e32 v112, 1.0, v108
	ds_read_b128 v[108:111], v65
	v_log_f32_e32 v124, v112
	ds_read_b128 v[112:115], v65 offset:16
	ds_read_b128 v[116:119], v65 offset:32
	ds_read_b128 v[120:123], v65 offset:48
	s_waitcnt lgkmcnt(3)
	v_fma_f32 v108, v98, v108, v96
	v_fmac_f32_e32 v108, v97, v109
	v_fmac_f32_e32 v108, v95, v110
	v_fmac_f32_e32 v108, v94, v111
	s_waitcnt lgkmcnt(2)
	v_fmac_f32_e32 v108, v26, v112
	v_fmac_f32_e32 v108, v23, v113
	v_fmac_f32_e32 v108, v27, v114
	v_fmac_f32_e32 v108, v25, v115
	s_waitcnt lgkmcnt(1)
	v_fmac_f32_e32 v108, v106, v116
	v_fmac_f32_e32 v108, v105, v117
	v_fmac_f32_e32 v108, v103, v118
	v_fmac_f32_e32 v108, v101, v119
	s_waitcnt lgkmcnt(0)
	v_fmac_f32_e32 v108, v99, v120
	v_fmac_f32_e32 v108, v104, v121
	v_fmac_f32_e32 v108, v102, v122
	v_fmac_f32_e32 v108, v100, v123
	v_mul_f32_e64 v109, |v108|, s27
	v_exp_f32_e32 v109, v109
	v_min_f32_e32 v110, 0, v126
	v_fmac_f32_e32 v110, 0xbf317218, v124
	v_fmac_f32_e32 v107, 0x3d800000, v110
	v_add_f32_e32 v109, 1.0, v109
	v_log_f32_e32 v112, v109
	v_min_f32_e32 v124, 0, v108
	ds_read_b128 v[108:111], v66
	ds_write_b32 v87, v107 offset:4096
	v_fmac_f32_e32 v124, 0xbf317218, v112
	ds_read_b128 v[112:115], v66 offset:16
	ds_read_b128 v[116:119], v66 offset:32
	ds_read_b128 v[120:123], v66 offset:48
	v_fmac_f32_e32 v107, 0x3d800000, v124
	s_waitcnt lgkmcnt(4)
	v_fma_f32 v108, v98, v108, v96
	v_fmac_f32_e32 v108, v97, v109
	v_fmac_f32_e32 v108, v95, v110
	v_fmac_f32_e32 v108, v94, v111
	s_waitcnt lgkmcnt(2)
	v_fmac_f32_e32 v108, v26, v112
	v_fmac_f32_e32 v108, v23, v113
	v_fmac_f32_e32 v108, v27, v114
	v_fmac_f32_e32 v108, v25, v115
	s_waitcnt lgkmcnt(1)
	v_fmac_f32_e32 v108, v106, v116
	v_fmac_f32_e32 v108, v105, v117
	v_fmac_f32_e32 v108, v103, v118
	v_fmac_f32_e32 v108, v101, v119
	s_waitcnt lgkmcnt(0)
	v_fmac_f32_e32 v108, v99, v120
	v_fmac_f32_e32 v108, v104, v121
	v_fmac_f32_e32 v108, v102, v122
	v_fmac_f32_e32 v108, v100, v123
	v_mul_f32_e64 v109, |v108|, s27
	v_exp_f32_e32 v109, v109
	v_min_f32_e32 v124, 0, v108
	ds_write_b32 v88, v107 offset:4096
	v_add_f32_e32 v112, 1.0, v109
	ds_read_b128 v[108:111], v67
	v_log_f32_e32 v125, v112
	ds_read_b128 v[112:115], v67 offset:16
	ds_read_b128 v[116:119], v67 offset:32
	ds_read_b128 v[120:123], v67 offset:48
	s_waitcnt lgkmcnt(3)
	v_fma_f32 v126, v98, v108, v96
	v_fmac_f32_e32 v126, v97, v109
	v_fmac_f32_e32 v126, v95, v110
	v_fmac_f32_e32 v126, v94, v111
	s_waitcnt lgkmcnt(2)
	v_fmac_f32_e32 v126, v26, v112
	v_fmac_f32_e32 v126, v23, v113
	v_fmac_f32_e32 v126, v27, v114
	v_fmac_f32_e32 v126, v25, v115
	s_waitcnt lgkmcnt(1)
	v_fmac_f32_e32 v126, v106, v116
	v_fmac_f32_e32 v126, v105, v117
	v_fmac_f32_e32 v126, v103, v118
	v_fmac_f32_e32 v126, v101, v119
	s_waitcnt lgkmcnt(0)
	v_fmac_f32_e32 v126, v99, v120
	v_fmac_f32_e32 v126, v104, v121
	v_fmac_f32_e32 v126, v102, v122
	v_fmac_f32_e32 v126, v100, v123
	v_mul_f32_e64 v108, |v126|, s27
	v_exp_f32_e32 v108, v108
	v_fmac_f32_e32 v124, 0xbf317218, v125
	v_fmac_f32_e32 v107, 0x3d800000, v124
	ds_write_b32 v89, v107 offset:4096
	v_add_f32_e32 v112, 1.0, v108
	ds_read_b128 v[108:111], v68
	v_log_f32_e32 v124, v112
	ds_read_b128 v[112:115], v68 offset:16
	ds_read_b128 v[116:119], v68 offset:32
	ds_read_b128 v[120:123], v68 offset:48
	s_waitcnt lgkmcnt(3)
	v_fma_f32 v125, v98, v108, v96
	v_fmac_f32_e32 v125, v97, v109
	v_fmac_f32_e32 v125, v95, v110
	v_fmac_f32_e32 v125, v94, v111
	s_waitcnt lgkmcnt(2)
	v_fmac_f32_e32 v125, v26, v112
	v_fmac_f32_e32 v125, v23, v113
	v_fmac_f32_e32 v125, v27, v114
	v_fmac_f32_e32 v125, v25, v115
	s_waitcnt lgkmcnt(1)
	v_fmac_f32_e32 v125, v106, v116
	v_fmac_f32_e32 v125, v105, v117
	v_fmac_f32_e32 v125, v103, v118
	v_fmac_f32_e32 v125, v101, v119
	s_waitcnt lgkmcnt(0)
	v_fmac_f32_e32 v125, v99, v120
	v_fmac_f32_e32 v125, v104, v121
	v_fmac_f32_e32 v125, v102, v122
	v_fmac_f32_e32 v125, v100, v123
	v_mul_f32_e64 v108, |v125|, s27
	v_exp_f32_e32 v108, v108
	v_min_f32_e32 v109, 0, v126
	v_fmac_f32_e32 v109, 0xbf317218, v124
	v_fmac_f32_e32 v107, 0x3d800000, v109
	v_add_f32_e32 v112, 1.0, v108
	ds_read_b128 v[108:111], v69
	v_log_f32_e32 v124, v112
	ds_read_b128 v[112:115], v69 offset:16
	ds_read_b128 v[116:119], v69 offset:32
	ds_read_b128 v[120:123], v69 offset:48
	ds_write_b32 v90, v107 offset:4096
	s_waitcnt lgkmcnt(4)
	v_fmac_f32_e32 v96, v98, v108
	v_fmac_f32_e32 v96, v97, v109
	v_fmac_f32_e32 v96, v95, v110
	v_fmac_f32_e32 v96, v94, v111
	s_waitcnt lgkmcnt(3)
	v_fmac_f32_e32 v96, v26, v112
	v_fmac_f32_e32 v96, v23, v113
	v_fmac_f32_e32 v96, v27, v114
	v_fmac_f32_e32 v96, v25, v115
	s_waitcnt lgkmcnt(2)
	v_fmac_f32_e32 v96, v106, v116
	v_fmac_f32_e32 v96, v105, v117
	v_fmac_f32_e32 v96, v103, v118
	v_fmac_f32_e32 v96, v101, v119
	s_waitcnt lgkmcnt(1)
	v_fmac_f32_e32 v96, v99, v120
	v_fmac_f32_e32 v96, v104, v121
	v_fmac_f32_e32 v96, v102, v122
	v_fmac_f32_e32 v96, v100, v123
	v_mul_f32_e64 v23, |v96|, s27
	v_exp_f32_e32 v23, v23
	v_min_f32_e32 v25, 0, v125
	v_fmac_f32_e32 v25, 0xbf317218, v124
	v_fmac_f32_e32 v107, 0x3d800000, v25
	v_add_f32_e32 v23, 1.0, v23
	v_log_f32_e32 v23, v23
	v_min_f32_e32 v25, 0, v96
	ds_write_b32 v91, v107 offset:4096
	v_fmac_f32_e32 v25, 0xbf317218, v23
	v_fmac_f32_e32 v107, 0x3d800000, v25
	ds_write_b32 v92, v107 offset:4096
	ds_write_b32 v192, v107 offset:36864
	s_waitcnt lgkmcnt(0)
	s_barrier
	s_and_saveexec_b64 s[14:15], s[6:7]
	s_cbranch_execz .LBB0_1245
	v_mov_b32_e32 v10, 0
	s_mov_b64 s[16:17], 0
	v_mov_b32_e32 v23, v53
	v_mov_b32_e32 v25, v196
